# v34: v32 + final RMSNorm loop de-serialised (norm weights loaded once, both rows' loads under one wait, no waits between stores)
# baseline (speedup 1.0000x reference)
; DI KA get_ka() { KA p = (KA)__builtin_amdgcn_kernarg_segment_ptr(); asm volatile("" : "+s"(p)); return p; }
; DI int opaque_tid() { int t = threadIdx.x; asm volatile("" : "+v"(t)); return t; }
; __global__ void __launch_bounds__(512, 2) hymba_fwd(Args a_unused) {
;     ...
;     {
;         const KA a = get_ka();
;         const int tid = opaque_tid(), wave = tid >> 6, lane = tid & 63, G = gridDim.x;
;         const float* nf = a->in[25];
;         const float* ssf = (const float*)(a->ws + WS_SS) + 6 * MPAD;
;         const bf16_t* XB = (const bf16_t*)(a->ws + WS_XB);
;         float* out = a->out;
;         for (int rowb = blockIdx.x * 8 + wave; rowb < MTOK; rowb += 2 * G * 8) {
.LBB0_1530:
	v_readlane_b32 s2, v254, 4
	v_readlane_b32 s3, v254, 5
	v_readlane_b32 s0, v254, 59
	v_ashrrev_i32_e32 v0, 6, v212
	s_movk_i32 s12, 0x4480
	v_add_u32_e32 v0, s0, v0
	v_cmp_gt_i32_e32 vcc, s12, v0
	s_and_saveexec_b64 s[0:1], vcc
	s_cbranch_execz .LBB0_1553
	s_load_dwordx4 s[4:7], s[2:3], 0xd0
	s_load_dwordx2 s[0:1], s[2:3], 0xc8
	v_and_b32_e32 v1, 63, v212
	v_mov_b32_e32 v17, 0
	v_lshlrev_b32_e32 v16, 4, v1
	s_waitcnt lgkmcnt(0)
	s_add_u32 s2, s6, 0x167800
	s_addc_u32 s3, s7, 0
	v_lshl_add_u64 v[2:3], s[6:7], 0, v[16:17]
	v_lshlrev_b32_e32 v16, 5, v1
	s_add_u32 s8, s4, 0x4000000
	s_mov_b64 s[6:7], 0x2d00000
	v_lshl_add_u64 v[22:23], s[0:1], 0, v[16:17]
	v_readlane_b32 s0, v254, 12
	v_mov_b32_e32 v16, v17
	s_addc_u32 s9, s5, 0
	v_lshl_add_u64 v[18:19], v[2:3], 0, s[6:7]
	v_lshlrev_b32_e32 v20, 3, v1
	v_add_u32_e32 v24, 0xffffbf80, v0
	s_lshl_b32 s13, s0, 4
	s_mov_b32 s14, 0
	s_mov_b64 s[6:7], 0
	s_movk_i32 s15, 0x407f
	s_mov_b32 s16, 0xfe03f81
	s_movk_i32 s17, 0xf7f0
	v_mov_b32_e32 v21, 0x358637bd
	s_mov_b32 s18, 0x800000
	s_movk_i32 s19, 0x447f
	v_mov_b64_e32 v[26:27], v[16:17]
	v_readlane_b32 s1, v254, 13
	global_load_dwordx4 v[48:51], v[22:23], off
	global_load_dwordx4 v[52:55], v[22:23], off offset:16
	global_load_dwordx4 v[56:59], v[22:23], off offset:2048
	global_load_dwordx4 v[60:63], v[22:23], off offset:2064
	s_branch .LBB0_1533

; __global__ void __launch_bounds__(512, 2) hymba_fwd(Args a_unused) {
;     ...
;             for (int q = 0; q < 2; ++q) {
;                 const int row = rowb + q * G * 8;
;                 dst[q] = nullptr;
;                 if (row < MP) { const int b = row / LP, t = row - b * LP; if (t >= NMETA) dst[q] = out + O_YP + ((size_t)b * SEQ + (t - NMETA)) * DM; }
;                 else if (row < MTOK) dst[q] = out + O_YS + (size_t)(row - MP) * DM;
;                 if (dst[q]) { rs[q] = rsqrtf(ssf[row] * (1.f / DM) + EPS); const u32x4* src = (const u32x4*)(XB + (size_t)row * DM); xr[q][0] = src[lane]; xr[q][1] = src[lane + 64]; }
;             }
.LBB0_1536:
	v_ashrrev_i32_e32 v31, 31, v30
	v_lshl_add_u64 v[8:9], v[30:31], 2, s[2:3]
	global_load_dword v64, v[8:9], off
	v_lshlrev_b64 v[8:9], 11, v[30:31]
	v_lshl_add_u64 v[30:31], v[18:19], 0, v[8:9]
	global_load_dwordx4 v[12:15], v[30:31], off
	global_load_dwordx4 v[8:11], v[30:31], off offset:1024

; __global__ void __launch_bounds__(512, 2) hymba_fwd(Args a_unused) {
;     ...
;             for (int q = 0; q < 2; ++q) {
;                 const int row = rowb + q * G * 8;
;                 dst[q] = nullptr;
;                 if (row < MP) { const int b = row / LP, t = row - b * LP; if (t >= NMETA) dst[q] = out + O_YP + ((size_t)b * SEQ + (t - NMETA)) * DM; }
;                 else if (row < MTOK) dst[q] = out + O_YS + (size_t)(row - MP) * DM;
;                 if (dst[q]) { rs[q] = rsqrtf(ssf[row] * (1.f / DM) + EPS); const u32x4* src = (const u32x4*)(XB + (size_t)row * DM); xr[q][0] = src[lane]; xr[q][1] = src[lane + 64]; }
;             }
.LBB0_1540:
	v_ashrrev_i32_e32 v33, 31, v32
	v_lshl_add_u64 v[0:1], v[32:33], 2, s[2:3]
	global_load_dword v65, v[0:1], off
	v_lshlrev_b64 v[0:1], 11, v[32:33]
	v_lshl_add_u64 v[32:33], v[18:19], 0, v[0:1]
	global_load_dwordx4 v[4:7], v[32:33], off
	global_load_dwordx4 v[0:3], v[32:33], off offset:1024
	s_or_b64 exec, exec, s[10:11]
	s_waitcnt vmcnt(0)
	v_cmp_ne_u64_e64 s[0:1], 0, v[28:29]
	s_and_saveexec_b64 s[10:11], s[0:1]
	s_cbranch_execnz .LBB0_1551

; __global__ void __launch_bounds__(512, 2) hymba_fwd(Args a_unused) {
;     ...
; #pragma unroll
;             for (int q = 0; q < 2; ++q) {
;                 if (dst[q]) {
; #pragma unroll
;                     for (int j = 0; j < 2; ++j) {
;                         const int c8 = (lane + 64 * j) * 8;
;                         float xv[8]; unpack8(xr[q][j], xv);
;                         const f32x4 n0 = *(const f32x4*)(nf + c8), n1 = *(const f32x4*)(nf + c8 + 4);
;                         const float r = rs[q];
;                         __builtin_nontemporal_store((f32x4){xv[0] * r * n0.x, xv[1] * r * n0.y, xv[2] * r * n0.z, xv[3] * r * n0.w}, (f32x4*)(dst[q] + c8));
;                         __builtin_nontemporal_store((f32x4){xv[4] * r * n1.x, xv[5] * r * n1.y, xv[6] * r * n1.z, xv[7] * r * n1.w}, (f32x4*)(dst[q] + c8 + 4));
;                     }
;                 }
;             }
.LBB0_1550:
	s_or_b64 exec, exec, s[10:11]
	s_waitcnt vmcnt(0)
	v_cmp_ne_u64_e64 s[0:1], 0, v[28:29]
	s_and_saveexec_b64 s[10:11], s[0:1]
	s_cbranch_execz .LBB0_1541
.LBB0_1551:
	v_fmamk_f32 v16, v64, 0x3a800000, v21
	v_rsq_f32_e32 v26, v16
	v_lshlrev_b32_e32 v40, 16, v12
	v_and_b32_e32 v41, 0xffff0000, v12
	v_lshlrev_b32_e32 v42, 16, v13
	v_and_b32_e32 v43, 0xffff0000, v13
	v_lshlrev_b32_e32 v44, 16, v14
	v_and_b32_e32 v45, 0xffff0000, v14
	v_lshlrev_b32_e32 v46, 16, v15
	v_and_b32_e32 v47, 0xffff0000, v15
	v_lshlrev_b32_e32 v16, 2, v20
	v_pk_mul_f32 v[40:41], v[26:27], v[40:41] op_sel_hi:[0,1]
	v_pk_mul_f32 v[42:43], v[26:27], v[42:43] op_sel_hi:[0,1]
	v_pk_mul_f32 v[44:45], v[26:27], v[44:45] op_sel_hi:[0,1]
	v_pk_mul_f32 v[46:47], v[26:27], v[46:47] op_sel_hi:[0,1]
	v_lshl_add_u64 v[28:29], v[28:29], 0, v[16:17]
	v_pk_mul_f32 v[32:33], v[48:49], v[40:41]
	v_pk_mul_f32 v[34:35], v[50:51], v[42:43]
	v_pk_mul_f32 v[36:37], v[52:53], v[44:45]
	v_pk_mul_f32 v[38:39], v[54:55], v[46:47]
	flat_store_dwordx4 v[28:29], v[32:35] nt
	flat_store_dwordx4 v[28:29], v[36:39] offset:16 nt
	v_lshlrev_b32_e32 v40, 16, v8
	v_and_b32_e32 v41, 0xffff0000, v8
	v_lshlrev_b32_e32 v42, 16, v9
	v_and_b32_e32 v43, 0xffff0000, v9
	v_lshlrev_b32_e32 v44, 16, v10
	v_and_b32_e32 v45, 0xffff0000, v10
	v_lshlrev_b32_e32 v46, 16, v11
	v_and_b32_e32 v47, 0xffff0000, v11
	v_pk_mul_f32 v[40:41], v[26:27], v[40:41] op_sel_hi:[0,1]
	v_pk_mul_f32 v[42:43], v[26:27], v[42:43] op_sel_hi:[0,1]
	v_pk_mul_f32 v[44:45], v[26:27], v[44:45] op_sel_hi:[0,1]
	v_pk_mul_f32 v[46:47], v[26:27], v[46:47] op_sel_hi:[0,1]
	v_pk_mul_f32 v[32:33], v[56:57], v[40:41]
	v_pk_mul_f32 v[34:35], v[58:59], v[42:43]
	v_pk_mul_f32 v[36:37], v[60:61], v[44:45]
	v_pk_mul_f32 v[38:39], v[62:63], v[46:47]
	flat_store_dwordx4 v[28:29], v[32:35] offset:2048 nt
	flat_store_dwordx4 v[28:29], v[36:39] offset:2064 nt
	s_or_b64 exec, exec, s[10:11]
	s_and_saveexec_b64 s[0:1], vcc
	s_cbranch_execz .LBB0_1532
.LBB0_1552:
	v_fmamk_f32 v16, v65, 0x3a800000, v21
	v_rsq_f32_e32 v27, v16
	v_lshlrev_b32_e32 v28, 16, v4
	v_and_b32_e32 v29, 0xffff0000, v4
	v_lshlrev_b32_e32 v40, 16, v5
	v_and_b32_e32 v41, 0xffff0000, v5
	v_lshlrev_b32_e32 v42, 16, v6
	v_and_b32_e32 v43, 0xffff0000, v6
	v_lshlrev_b32_e32 v44, 16, v7
	v_and_b32_e32 v45, 0xffff0000, v7
	v_lshlrev_b32_e32 v16, 2, v20
	v_pk_mul_f32 v[28:29], v[26:27], v[28:29] op_sel:[1,0]
	v_pk_mul_f32 v[40:41], v[26:27], v[40:41] op_sel:[1,0]
	v_pk_mul_f32 v[42:43], v[26:27], v[42:43] op_sel:[1,0]
	v_pk_mul_f32 v[44:45], v[26:27], v[44:45] op_sel:[1,0]
	v_lshl_add_u64 v[46:47], v[30:31], 0, v[16:17]
	v_pk_mul_f32 v[28:29], v[48:49], v[28:29]
	v_pk_mul_f32 v[30:31], v[50:51], v[40:41]
	v_pk_mul_f32 v[32:33], v[52:53], v[42:43]
	v_pk_mul_f32 v[34:35], v[54:55], v[44:45]
	flat_store_dwordx4 v[46:47], v[28:31] nt
	flat_store_dwordx4 v[46:47], v[32:35] offset:16 nt
	v_lshlrev_b32_e32 v36, 16, v0
	v_and_b32_e32 v37, 0xffff0000, v0
	v_lshlrev_b32_e32 v38, 16, v1
	v_and_b32_e32 v39, 0xffff0000, v1
	v_lshlrev_b32_e32 v40, 16, v2
	v_and_b32_e32 v41, 0xffff0000, v2
	v_lshlrev_b32_e32 v42, 16, v3
	v_and_b32_e32 v43, 0xffff0000, v3
	v_pk_mul_f32 v[36:37], v[26:27], v[36:37] op_sel:[1,0]
	v_pk_mul_f32 v[38:39], v[26:27], v[38:39] op_sel:[1,0]
	v_pk_mul_f32 v[40:41], v[26:27], v[40:41] op_sel:[1,0]
	v_pk_mul_f32 v[42:43], v[26:27], v[42:43] op_sel:[1,0]
	v_pk_mul_f32 v[28:29], v[56:57], v[36:37]
	v_pk_mul_f32 v[30:31], v[58:59], v[38:39]
	v_pk_mul_f32 v[32:33], v[60:61], v[40:41]
	v_pk_mul_f32 v[34:35], v[62:63], v[42:43]
	flat_store_dwordx4 v[46:47], v[28:31] offset:2048 nt
	flat_store_dwordx4 v[46:47], v[32:35] offset:2064 nt
	s_branch .LBB0_1532
